# prologue de-serialisation in the proj GEMM: per-phase rstd table computed after the first eight LDS-DMA tile loads are in flight, one wave per unit with dwordx4 plane loads instead of 3 serial iterati
# speedup vs baseline: 1.0065x; 1.0065x over previous
.LBB0_476:
	s_load_dword s18, s[88:89], 0x0
	s_waitcnt vmcnt(0)
	v_lshlrev_b32_e32 v10, 2, v248
	v_ashrrev_i32_e32 v6, 8, v248
	v_and_b32_e32 v0, 0x3fc, v10
	s_waitcnt vmcnt(4) lgkmcnt(0)
	v_lshl_add_u64 v[2:3], s[14:15], 0, v[0:1]
	s_ashr_i32 s19, s18, 31
	v_lshl_or_b32 v0, v6, 10, v0
	v_readlane_b32 s4, v254, 57
	v_mov_b64_e32 v[4:5], s[2:3]
	s_lshl_b64 s[20:21], s[18:19], 1
	v_add_u32_e32 v0, s4, v0
	v_mad_i64_i32 v[4:5], s[4:5], s18, v6, v[4:5]
	s_mov_b64 s[14:15], 0
.LBB0_480:
	s_or_b64 exec, exec, s[14:15]
	v_readlane_b32 s4, v254, 4
	v_readlane_b32 s5, v254, 5
	v_readfirstlane_b32 s20, v248
	s_andn2_b64 vcc, exec, s[4:5]
	s_mov_b32 s44, s62
	s_waitcnt lgkmcnt(0)
	s_barrier
	s_cbranch_vccnz .LBB0_496
	v_lshlrev_b32_e32 v0, 4, v248
	v_add_u32_e32 v2, 0x2000, v0
	v_ashrrev_i32_e32 v3, 31, v2
	v_lshrrev_b32_e32 v3, 22, v3
	v_add_u32_e32 v3, v2, v3
	v_ashrrev_i32_e32 v11, 10, v3
	v_mul_i32_i24_e32 v4, 0x400, v11
	v_sub_u32_e32 v2, v2, v4
	v_lshrrev_b32_e32 v4, 4, v2
	v_bitop3_b32 v2, v4, v2, 32 bitop3:0x6c
	v_ashrrev_i32_e32 v4, 31, v2
	v_lshrrev_b32_e32 v4, 26, v4
	v_add_u32_e32 v4, v2, v4
	v_ashrrev_i32_e32 v12, 6, v4
	v_and_b32_e32 v4, 0xc0, v4
	v_sub_u32_e32 v2, v2, v4
	v_lshlrev_b32_e32 v3, 5, v11
	v_ashrrev_i16_sdwa v2, v214, sext(v2) dst_sel:DWORD dst_unused:UNUSED_PAD src0_sel:DWORD src1_sel:BYTE_0
	s_ashr_i32 s22, s20, 6
	v_and_b32_e32 v3, 32, v3
	v_bfe_i32 v13, v2, 0, 16
	s_ashr_i32 s21, s20, 8
	s_lshl_b32 s38, s22, 10
	s_mul_i32 s5, s16, 0x600000
	v_add_lshl_u32 v2, v3, v13, 1
	v_lshlrev_b32_e32 v3, 3, v11
	s_mul_hi_i32 s4, s16, 0x600000
	s_add_u32 s39, s8, s5
	v_and_b32_e32 v3, -16, v3
	s_addc_u32 s42, s9, s4
	v_add_u32_e32 v3, v12, v3
	v_and_b32_e32 v4, 3, v12
	s_mov_b32 s4, 0x1fffe0
	v_lshl_add_u32 v130, v3, 11, v2
	v_and_or_b32 v4, v3, s4, v4
	v_lshrrev_b32_e32 v5, 2, v3
	v_lshlrev_b32_e32 v3, 1, v3
	v_and_b32_e32 v5, 4, v5
	v_and_b32_e32 v3, 24, v3
	v_or3_b32 v3, v4, v5, v3
	v_lshl_add_u32 v132, v3, 11, v2
	v_bfe_i32 v3, v248, 27, 1
	v_lshrrev_b32_e32 v3, 22, v3
	v_add_u32_e32 v3, v0, v3
	v_and_b32_e32 v3, 0xfffffc00, v3
	v_sub_u32_e32 v0, v0, v3
	v_lshrrev_b32_e32 v3, 4, v0
	v_bitop3_b32 v0, v3, v0, 32 bitop3:0x6c
	v_ashrrev_i32_e32 v3, 31, v0
	v_ashrrev_i32_e32 v2, 31, v248
	v_lshrrev_b32_e32 v3, 26, v3
	v_lshrrev_b32_e32 v2, 26, v2
	v_add_u32_e32 v3, v0, v3
	v_add_u32_e32 v2, v248, v2
	v_ashrrev_i32_e32 v15, 6, v3
	v_and_b32_e32 v3, 0xc0, v3
	v_ashrrev_i32_e32 v14, 6, v2
	v_sub_u32_e32 v0, v0, v3
	v_lshlrev_b32_e32 v2, 5, v14
	v_ashrrev_i16_sdwa v0, v214, sext(v0) dst_sel:DWORD dst_unused:UNUSED_PAD src0_sel:DWORD src1_sel:BYTE_0
	v_and_b32_e32 v2, 32, v2
	v_bfe_i32 v16, v0, 0, 16
	v_add_lshl_u32 v0, v2, v16, 1
	v_lshlrev_b32_e32 v2, 3, v14
	v_and_b32_e32 v2, -16, v2
	v_add_u32_e32 v2, v15, v2
	v_and_b32_e32 v3, 3, v15
	v_lshl_add_u32 v134, v2, 11, v0
	v_and_or_b32 v3, v2, s4, v3
	v_lshrrev_b32_e32 v4, 2, v2
	v_lshlrev_b32_e32 v2, 1, v2
	v_readlane_b32 s4, v254, 45
	v_and_b32_e32 v4, 4, v4
	v_and_b32_e32 v2, 24, v2
	v_readlane_b32 s5, v254, 46
	s_add_u32 s34, s39, s4
	v_or3_b32 v2, v3, v4, v2
	s_addc_u32 s35, s42, s5
	s_add_i32 s43, s38, 0
	v_lshl_add_u32 v0, v2, 11, v0
	s_add_i32 m0, s43, 0x10000
	v_mov_b32_e32 v133, v1
	global_load_lds_dwordx4 v0, s[34:35]
	s_add_i32 m0, s43, 0x12000
	s_add_u32 s4, s34, 0x40000
	global_load_lds_dwordx4 v132, s[34:35]
	s_addc_u32 s5, s35, 0
	s_add_i32 m0, s43, 0x14000
	v_mov_b32_e32 v135, v1
	global_load_lds_dwordx4 v0, s[4:5]
	s_add_i32 m0, s43, 0x16000
	v_mov_b32_e32 v131, v1
	global_load_lds_dwordx4 v132, s[4:5]
	v_readlane_b32 s4, v255, 0
	v_readlane_b32 s5, v255, 1
	s_add_u32 s30, s12, s4
	s_addc_u32 s31, s13, s5
	s_add_i32 s44, s43, 0x2000
	s_mov_b32 m0, s43
	s_add_u32 s4, s30, 0x40000
	global_load_lds_dwordx4 v134, s[30:31]
	s_mov_b32 m0, s44
	s_addc_u32 s5, s31, 0
	s_add_i32 s45, s43, 0x4000
	global_load_lds_dwordx4 v130, s[30:31]
	s_mov_b32 m0, s45
	s_add_i32 s46, s43, 0x6000
	global_load_lds_dwordx4 v134, s[4:5]
	s_mov_b32 m0, s46
	s_cmp_eq_u32 s21, 1
	global_load_lds_dwordx4 v130, s[4:5]
	v_lshl_add_u64 v[8:9], s[34:35], 0, v[0:1]
	v_lshl_add_u64 v[6:7], s[34:35], 0, v[132:133]
	v_lshl_add_u64 v[2:3], s[30:31], 0, v[134:135]
	s_cselect_b64 s[14:15], -1, 0
	s_cmp_lg_u32 s21, 1
	v_lshl_add_u64 v[4:5], s[30:31], 0, v[130:131]
	s_cbranch_scc1 .LBB0_483
	s_barrier
.LBB0_483:
	s_cmp_gt_u32 s22, 5
	s_cbranch_scc1 .Lpt_done
	s_lshl_b32 s6, s22, 8
	s_add_i32 s6, s6, s2
	s_and_b32 s7, s6, 7
	s_mul_i32 s7, s7, 0xc0
	s_lshr_b32 s6, s6, 3
	s_add_i32 s7, s7, s6
	s_lshr_b32 s6, s7, 4
	s_mul_i32 s6, s6, 0x5556
	s_lshr_b32 s6, s6, 16
	s_mul_i32 s4, s6, 48
	s_sub_i32 s7, s7, s4
	s_and_b32 s7, s7, 3
	s_lshl_b32 s6, s6, 2
	s_add_i32 s6, s6, s7
	s_lshl_b32 s6, s6, 10
	v_lshlrev_b32_e32 v20, 4, v213
	v_add_u32_e32 v21, s6, v20
	s_add_u32 s4, s8, 0x17100000
	s_addc_u32 s5, s9, 0
	global_load_dwordx4 v[24:27], v21, s[4:5]
	v_add_u32_e32 v21, 0x20000, v21
	global_load_dwordx4 v[28:31], v21, s[4:5]
	v_add_u32_e32 v21, 0x20000, v21
	global_load_dwordx4 v[32:35], v21, s[4:5]
	v_add_u32_e32 v21, 0x20000, v21
	global_load_dwordx4 v[36:39], v21, s[4:5]
	v_add_u32_e32 v21, 0x20000, v21
	global_load_dwordx4 v[40:43], v21, s[4:5]
	v_add_u32_e32 v21, 0x20000, v21
	global_load_dwordx4 v[44:47], v21, s[4:5]
	v_add_u32_e32 v21, 0x20000, v21
	global_load_dwordx4 v[48:51], v21, s[4:5]
	v_add_u32_e32 v21, 0x20000, v21
	global_load_dwordx4 v[52:55], v21, s[4:5]
	v_add_u32_e32 v21, 0x20000, v21
	global_load_dwordx4 v[56:59], v21, s[4:5]
	v_add_u32_e32 v21, 0x20000, v21
	global_load_dwordx4 v[60:63], v21, s[4:5]
	v_add_u32_e32 v21, 0x20000, v21
	global_load_dwordx4 v[64:67], v21, s[4:5]
	v_add_u32_e32 v21, 0x20000, v21
	global_load_dwordx4 v[68:71], v21, s[4:5]
	v_add_u32_e32 v21, 0x20000, v21
	global_load_dwordx4 v[72:75], v21, s[4:5]
	v_add_u32_e32 v21, 0x20000, v21
	global_load_dwordx4 v[76:79], v21, s[4:5]
	v_add_u32_e32 v21, 0x20000, v21
	global_load_dwordx4 v[80:83], v21, s[4:5]
	v_add_u32_e32 v21, 0x20000, v21
	global_load_dwordx4 v[84:87], v21, s[4:5]
	s_waitcnt vmcnt(0)
	v_pk_add_f32 v[24:25], v[24:25], v[28:29]
	v_pk_add_f32 v[26:27], v[26:27], v[30:31]
	v_pk_add_f32 v[24:25], v[24:25], v[32:33]
	v_pk_add_f32 v[26:27], v[26:27], v[34:35]
	v_pk_add_f32 v[24:25], v[24:25], v[36:37]
	v_pk_add_f32 v[26:27], v[26:27], v[38:39]
	v_pk_add_f32 v[24:25], v[24:25], v[40:41]
	v_pk_add_f32 v[26:27], v[26:27], v[42:43]
	v_pk_add_f32 v[24:25], v[24:25], v[44:45]
	v_pk_add_f32 v[26:27], v[26:27], v[46:47]
	v_pk_add_f32 v[24:25], v[24:25], v[48:49]
	v_pk_add_f32 v[26:27], v[26:27], v[50:51]
	v_pk_add_f32 v[24:25], v[24:25], v[52:53]
	v_pk_add_f32 v[26:27], v[26:27], v[54:55]
	v_pk_add_f32 v[24:25], v[24:25], v[56:57]
	v_pk_add_f32 v[26:27], v[26:27], v[58:59]
	v_pk_add_f32 v[24:25], v[24:25], v[60:61]
	v_pk_add_f32 v[26:27], v[26:27], v[62:63]
	v_pk_add_f32 v[24:25], v[24:25], v[64:65]
	v_pk_add_f32 v[26:27], v[26:27], v[66:67]
	v_pk_add_f32 v[24:25], v[24:25], v[68:69]
	v_pk_add_f32 v[26:27], v[26:27], v[70:71]
	v_pk_add_f32 v[24:25], v[24:25], v[72:73]
	v_pk_add_f32 v[26:27], v[26:27], v[74:75]
	v_pk_add_f32 v[24:25], v[24:25], v[76:77]
	v_pk_add_f32 v[26:27], v[26:27], v[78:79]
	v_pk_add_f32 v[24:25], v[24:25], v[80:81]
	v_pk_add_f32 v[26:27], v[26:27], v[82:83]
	v_pk_add_f32 v[24:25], v[24:25], v[84:85]
	v_pk_add_f32 v[26:27], v[26:27], v[86:87]
	v_fmamk_f32 v24, v24, 0x3a800000, v212
	v_fmamk_f32 v25, v25, 0x3a800000, v212
	v_fmamk_f32 v26, v26, 0x3a800000, v212
	v_fmamk_f32 v27, v27, 0x3a800000, v212
	v_rsq_f32_e32 v24, v24
	v_rsq_f32_e32 v25, v25
	v_rsq_f32_e32 v26, v26
	v_rsq_f32_e32 v27, v27
	v_readlane_b32 s6, v254, 57
	s_lshl_b32 s7, s22, 10
	s_nop 1
	s_add_i32 s6, s6, s7
	v_add_u32_e32 v21, s6, v20
	s_nop 0
	ds_write_b128 v21, v[24:27]
